# MLA loop: LDS fragment lookahead 4 instead of 8 (smaller post-barrier LDS burst)
# speedup vs baseline: 1.0038x; 1.0025x over previous
.LBB0_562:
	s_mul_i32 s0, s22, 0xa000
	v_add_u32_e32 v204, s0, v178
	v_add_u32_e32 v205, s0, v180
	v_add_u32_e32 v189, s0, v181
	v_add_u32_e32 v188, s0, v182
	ds_read_b128 v[208:211], v204
	ds_read_b128 v[212:215], v205
	ds_read_b128 v[216:219], v189
	ds_read_b128 v[220:223], v188
	v_add_u32_e32 v199, s0, v184
	v_add_u32_e32 v200, s0, v185
	v_add_u32_e32 v201, s0, v186
	v_add_u32_e32 v207, s0, v187
	s_waitcnt lgkmcnt(3)
	v_mfma_f32_32x32x16_bf16 v[96:111], v[208:211], v[112:115], v[64:79]
	ds_read_b128 v[224:227], v204 offset:128
	s_waitcnt lgkmcnt(3)
	v_mfma_f32_32x32x16_bf16 v[96:111], v[212:215], v[116:119], v[96:111]
	ds_read_b128 v[228:231], v205 offset:128
	s_waitcnt lgkmcnt(3)
	v_mfma_f32_32x32x16_bf16 v[96:111], v[216:219], v[120:123], v[96:111]
	ds_read_b128 v[232:235], v189 offset:128
	s_waitcnt lgkmcnt(3)
	v_mfma_f32_32x32x16_bf16 v[96:111], v[220:223], v[124:127], v[96:111]
	ds_read_b128 v[236:239], v188 offset:128
	s_waitcnt lgkmcnt(3)
	v_mfma_f32_32x32x16_bf16 v[96:111], v[224:227], v[128:131], v[96:111]
	ds_read_b128 v[240:243], v204 offset:256
	s_waitcnt lgkmcnt(3)
	v_mfma_f32_32x32x16_bf16 v[96:111], v[228:231], v[132:135], v[96:111]
	ds_read_b128 v[248:251], v205 offset:256
	s_waitcnt lgkmcnt(3)
	v_mfma_f32_32x32x16_bf16 v[96:111], v[232:235], v[136:139], v[96:111]
	ds_read_b128 v[208:211], v189 offset:256
	s_waitcnt lgkmcnt(3)
	v_mfma_f32_32x32x16_bf16 v[96:111], v[236:239], v[140:143], v[96:111]
	ds_read_b128 v[212:215], v188 offset:256
	s_waitcnt lgkmcnt(3)
	v_mfma_f32_32x32x16_bf16 v[96:111], v[240:243], v[144:147], v[96:111]
	ds_read_b128 v[216:219], v199 offset:24576
	s_waitcnt lgkmcnt(3)
	v_mfma_f32_32x32x16_bf16 v[96:111], v[248:251], v[148:151], v[96:111]
	ds_read_b128 v[220:223], v199 offset:28672
	s_waitcnt lgkmcnt(3)
	v_mfma_f32_32x32x16_bf16 v[96:111], v[208:211], v[152:155], v[96:111]
	ds_read_b128 v[224:227], v199 offset:32768
	s_waitcnt lgkmcnt(3)
	v_mfma_f32_32x32x16_bf16 v[96:111], v[212:215], v[156:159], v[96:111]
	ds_read_b128 v[228:231], v199 offset:36864
	s_add_i32 s0, s22, 1
	s_cmp_lg_u32 s22, 2
	s_cselect_b32 s22, s0, 0
	s_add_i32 s0, s15, 1
	s_cmp_lg_u32 s15, 2
	s_cselect_b32 s15, s0, 0
	s_nop 4
	v_max_f32_e32 v80, v97, v97
	v_max_f32_e32 v81, v96, v96
	v_max_f32_e32 v80, v81, v80
	v_max3_f32 v80, v80, v98, v99
	v_max3_f32 v80, v80, v100, v101
	v_max3_f32 v80, v80, v102, v103
	v_max3_f32 v80, v80, v104, v105
	v_max3_f32 v80, v80, v106, v107
	v_max3_f32 v80, v80, v108, v109
	v_max3_f32 v206, v80, v110, v111
	v_cmp_ge_f32_e32 vcc, s85, v206
	s_cmp_eq_u64 vcc, exec
	s_cbranch_scc1 .Lmla_a_norescale
	ds_bpermute_b32 v64, v183, v206
	s_waitcnt lgkmcnt(0)
	v_max3_f32 v64, v206, v64, 0
	v_exp_f32_e64 v66, -v64
	v_add_f32_e32 v165, v165, v64
	v_xor_b32_e32 v80, 0x80000000, v165
	v_pk_add_f32 v[96:97], v[96:97], v[64:65] op_sel_hi:[1,0] neg_lo:[0,1] neg_hi:[0,1]
	v_mul_f32_e32 v164, v164, v66
	v_pk_mul_f32 v[14:15], v[14:15], v[66:67] op_sel_hi:[1,0]
	v_pk_mul_f32 v[12:13], v[12:13], v[66:67] op_sel_hi:[1,0]
	v_pk_mul_f32 v[10:11], v[10:11], v[66:67] op_sel_hi:[1,0]
	v_pk_mul_f32 v[8:9], v[8:9], v[66:67] op_sel_hi:[1,0]
	v_pk_mul_f32 v[6:7], v[6:7], v[66:67] op_sel_hi:[1,0]
	v_pk_mul_f32 v[4:5], v[4:5], v[66:67] op_sel_hi:[1,0]
	v_pk_mul_f32 v[2:3], v[2:3], v[66:67] op_sel_hi:[1,0]
	v_pk_mul_f32 v[0:1], v[0:1], v[66:67] op_sel_hi:[1,0]
	v_pk_mul_f32 v[30:31], v[30:31], v[66:67] op_sel_hi:[1,0]
	v_pk_mul_f32 v[28:29], v[28:29], v[66:67] op_sel_hi:[1,0]
	v_pk_mul_f32 v[26:27], v[26:27], v[66:67] op_sel_hi:[1,0]
	v_pk_mul_f32 v[24:25], v[24:25], v[66:67] op_sel_hi:[1,0]
	v_pk_mul_f32 v[22:23], v[22:23], v[66:67] op_sel_hi:[1,0]
	v_pk_mul_f32 v[20:21], v[20:21], v[66:67] op_sel_hi:[1,0]
	v_pk_mul_f32 v[18:19], v[18:19], v[66:67] op_sel_hi:[1,0]
	v_pk_mul_f32 v[16:17], v[16:17], v[66:67] op_sel_hi:[1,0]
	v_pk_mul_f32 v[46:47], v[46:47], v[66:67] op_sel_hi:[1,0]
	v_pk_mul_f32 v[44:45], v[44:45], v[66:67] op_sel_hi:[1,0]
	v_pk_mul_f32 v[42:43], v[42:43], v[66:67] op_sel_hi:[1,0]
	v_pk_mul_f32 v[40:41], v[40:41], v[66:67] op_sel_hi:[1,0]
	v_pk_mul_f32 v[38:39], v[38:39], v[66:67] op_sel_hi:[1,0]
	v_pk_mul_f32 v[36:37], v[36:37], v[66:67] op_sel_hi:[1,0]
	v_pk_mul_f32 v[34:35], v[34:35], v[66:67] op_sel_hi:[1,0]
	v_pk_mul_f32 v[32:33], v[32:33], v[66:67] op_sel_hi:[1,0]
	v_pk_mul_f32 v[62:63], v[62:63], v[66:67] op_sel_hi:[1,0]
	v_pk_mul_f32 v[60:61], v[60:61], v[66:67] op_sel_hi:[1,0]
	v_pk_mul_f32 v[58:59], v[58:59], v[66:67] op_sel_hi:[1,0]
	v_pk_mul_f32 v[56:57], v[56:57], v[66:67] op_sel_hi:[1,0]
	v_pk_mul_f32 v[54:55], v[54:55], v[66:67] op_sel_hi:[1,0]
	v_pk_mul_f32 v[52:53], v[52:53], v[66:67] op_sel_hi:[1,0]
	v_pk_mul_f32 v[50:51], v[50:51], v[66:67] op_sel_hi:[1,0]
	v_pk_mul_f32 v[48:49], v[48:49], v[66:67] op_sel_hi:[1,0]
	v_pk_add_f32 v[98:99], v[98:99], v[64:65] op_sel_hi:[1,0] neg_lo:[0,1] neg_hi:[0,1]
	v_pk_add_f32 v[100:101], v[100:101], v[64:65] op_sel_hi:[1,0] neg_lo:[0,1] neg_hi:[0,1]
	v_pk_add_f32 v[102:103], v[102:103], v[64:65] op_sel_hi:[1,0] neg_lo:[0,1] neg_hi:[0,1]
	v_pk_add_f32 v[104:105], v[104:105], v[64:65] op_sel_hi:[1,0] neg_lo:[0,1] neg_hi:[0,1]
	v_pk_add_f32 v[106:107], v[106:107], v[64:65] op_sel_hi:[1,0] neg_lo:[0,1] neg_hi:[0,1]
	v_pk_add_f32 v[108:109], v[108:109], v[64:65] op_sel_hi:[1,0] neg_lo:[0,1] neg_hi:[0,1]
	v_pk_add_f32 v[110:111], v[110:111], v[64:65] op_sel_hi:[1,0] neg_lo:[0,1] neg_hi:[0,1]
	v_mov_b32_e32 v64, v80
	v_mov_b32_e32 v65, v80
	v_mov_b32_e32 v66, v80
	v_mov_b32_e32 v67, v80
	v_mov_b32_e32 v68, v80
	v_mov_b32_e32 v69, v80
	v_mov_b32_e32 v70, v80
	v_mov_b32_e32 v71, v80
	v_mov_b32_e32 v72, v80
	v_mov_b32_e32 v73, v80
	v_mov_b32_e32 v74, v80
	v_mov_b32_e32 v75, v80
	v_mov_b32_e32 v76, v80
	v_mov_b32_e32 v77, v80
	v_mov_b32_e32 v78, v80
	v_mov_b32_e32 v79, v80
.Lmla_a_norescale:
	v_exp_f32_e32 v96, v96
	v_exp_f32_e32 v97, v97
	v_exp_f32_e32 v98, v98
	v_exp_f32_e32 v99, v99
	v_add_f32_e32 v192, 0, v96
	v_exp_f32_e32 v193, v100
	v_add_f32_e32 v192, v97, v192
	v_add_f32_e32 v192, v98, v192
	v_add_f32_e32 v192, v99, v192
	v_exp_f32_e32 v101, v101
	v_add_f32_e32 v100, v193, v192
	v_exp_f32_e32 v192, v102
	v_exp_f32_e32 v194, v103
	v_exp_f32_e32 v195, v104
	v_add_f32_e32 v100, v101, v100
	v_exp_f32_e32 v198, v105
	v_add_f32_e32 v100, v192, v100
	v_exp_f32_e32 v106, v106
	v_add_f32_e32 v100, v194, v100
	v_exp_f32_e32 v107, v107
	v_add_f32_e32 v100, v195, v100
	v_exp_f32_e32 v108, v108
	v_add_f32_e32 v100, v198, v100
	v_exp_f32_e32 v109, v109
	v_add_f32_e32 v100, v106, v100
	v_add_f32_e32 v100, v107, v100
	v_add_f32_e32 v100, v108, v100
	v_cvt_pk_bf16_f32 v104, v193, v101
	v_add_f32_e32 v100, v109, v100
	v_cvt_pk_bf16_f32 v102, v96, v97
	v_cvt_pk_bf16_f32 v103, v98, v99
	v_cvt_pk_bf16_f32 v97, v106, v107
	v_cvt_pk_bf16_f32 v98, v108, v109
	v_cvt_pk_bf16_f32 v105, v192, v194
	v_exp_f32_e32 v110, v110
	v_exp_f32_e32 v111, v111
	v_cvt_pk_bf16_f32 v96, v195, v198
	v_cvt_pk_bf16_f32 v99, v110, v111
	v_add_f32_e32 v100, v110, v100
	v_add_f32_e32 v100, v111, v100
	s_waitcnt lgkmcnt(3)
	v_mfma_f32_32x32x16_bf16 v[48:63], v[216:219], v[102:105], v[48:63]
	ds_read_b128 v[232:235], v200 offset:24576
	s_waitcnt lgkmcnt(3)
	v_mfma_f32_32x32x16_bf16 v[32:47], v[220:223], v[102:105], v[32:47]
	ds_read_b128 v[236:239], v200 offset:28672
	s_waitcnt lgkmcnt(3)
	v_mfma_f32_32x32x16_bf16 v[16:31], v[224:227], v[102:105], v[16:31]
	ds_read_b128 v[240:243], v200 offset:32768
	s_waitcnt lgkmcnt(3)
	v_mfma_f32_32x32x16_bf16 v[0:15], v[228:231], v[102:105], v[0:15]
	ds_read_b128 v[248:251], v200 offset:36864
	s_waitcnt lgkmcnt(3)
	v_mfma_f32_32x32x16_bf16 v[48:63], v[232:235], v[96:99], v[48:63]
	ds_read_b128 v[208:211], v204 offset:12288
	s_waitcnt lgkmcnt(3)
	v_mfma_f32_32x32x16_bf16 v[32:47], v[236:239], v[96:99], v[32:47]
	ds_read_b128 v[212:215], v205 offset:12288
	s_waitcnt lgkmcnt(3)
	v_mfma_f32_32x32x16_bf16 v[16:31], v[240:243], v[96:99], v[16:31]
	ds_read_b128 v[216:219], v189 offset:12288
	s_waitcnt lgkmcnt(3)
	v_mfma_f32_32x32x16_bf16 v[0:15], v[248:251], v[96:99], v[0:15]
	ds_read_b128 v[220:223], v188 offset:12288
	s_waitcnt lgkmcnt(3)
	v_mfma_f32_32x32x16_bf16 v[80:95], v[208:211], v[112:115], v[64:79]
	ds_read_b128 v[224:227], v204 offset:12416
	s_waitcnt lgkmcnt(3)
	v_mfma_f32_32x32x16_bf16 v[80:95], v[212:215], v[116:119], v[80:95]
	ds_read_b128 v[228:231], v205 offset:12416
	s_waitcnt lgkmcnt(3)
	v_mfma_f32_32x32x16_bf16 v[80:95], v[216:219], v[120:123], v[80:95]
	ds_read_b128 v[232:235], v189 offset:12416
	s_waitcnt lgkmcnt(3)
	v_mfma_f32_32x32x16_bf16 v[80:95], v[220:223], v[124:127], v[80:95]
	ds_read_b128 v[236:239], v188 offset:12416
	s_waitcnt lgkmcnt(3)
	v_mfma_f32_32x32x16_bf16 v[80:95], v[224:227], v[128:131], v[80:95]
	ds_read_b128 v[240:243], v204 offset:12544
	s_waitcnt lgkmcnt(3)
	v_mfma_f32_32x32x16_bf16 v[80:95], v[228:231], v[132:135], v[80:95]
	ds_read_b128 v[248:251], v205 offset:12544
	s_waitcnt lgkmcnt(3)
	v_mfma_f32_32x32x16_bf16 v[80:95], v[232:235], v[136:139], v[80:95]
	ds_read_b128 v[208:211], v189 offset:12544
	s_waitcnt lgkmcnt(3)
	v_mfma_f32_32x32x16_bf16 v[80:95], v[236:239], v[140:143], v[80:95]
	ds_read_b128 v[212:215], v188 offset:12544
	s_waitcnt lgkmcnt(3)
	v_mfma_f32_32x32x16_bf16 v[80:95], v[240:243], v[144:147], v[80:95]
	ds_read_b128 v[216:219], v201 offset:24576
	s_waitcnt lgkmcnt(3)
	v_mfma_f32_32x32x16_bf16 v[80:95], v[248:251], v[148:151], v[80:95]
	ds_read_b128 v[220:223], v201 offset:28672
	s_waitcnt lgkmcnt(3)
	v_mfma_f32_32x32x16_bf16 v[80:95], v[208:211], v[152:155], v[80:95]
	ds_read_b128 v[224:227], v201 offset:32768
	s_waitcnt lgkmcnt(3)
	v_mfma_f32_32x32x16_bf16 v[80:95], v[212:215], v[156:159], v[80:95]
	ds_read_b128 v[228:231], v201 offset:36864
	v_lshl_add_u64 v[166:167], v[166:167], 0, s[66:67]
	v_lshl_add_u64 v[168:169], v[168:169], 0, v[162:163]
	v_lshl_add_u64 v[170:171], v[170:171], 0, v[160:161]
	v_lshl_add_u64 v[172:173], v[172:173], 0, v[176:177]
	s_nop 7
	v_max_f32_e32 v96, v81, v81
	v_max_f32_e32 v97, v80, v80
	v_max_f32_e32 v96, v97, v96
	v_max3_f32 v96, v96, v82, v83
	v_max3_f32 v96, v96, v84, v85
	v_max3_f32 v96, v96, v86, v87
	v_max3_f32 v96, v96, v88, v89
	v_max3_f32 v96, v96, v90, v91
	v_max3_f32 v96, v96, v92, v93
	v_max3_f32 v97, v96, v94, v95
	v_cmp_ge_f32_e32 vcc, s85, v97
	v_add_f32_e32 v96, v164, v100
	s_cmp_eq_u64 vcc, exec
	s_cbranch_scc1 .Lmla_b_norescale
	ds_bpermute_b32 v64, v183, v97
	s_waitcnt lgkmcnt(0)
	v_max3_f32 v66, v97, v64, 0
	v_exp_f32_e64 v68, -v66
	v_add_f32_e32 v165, v165, v66
	v_xor_b32_e32 v64, 0x80000000, v165
	v_pk_add_f32 v[80:81], v[80:81], v[66:67] op_sel_hi:[1,0] neg_lo:[0,1] neg_hi:[0,1]
	v_pk_mul_f32 v[62:63], v[62:63], v[68:69] op_sel_hi:[1,0]
	v_pk_mul_f32 v[60:61], v[60:61], v[68:69] op_sel_hi:[1,0]
	v_pk_mul_f32 v[58:59], v[58:59], v[68:69] op_sel_hi:[1,0]
	v_pk_mul_f32 v[56:57], v[56:57], v[68:69] op_sel_hi:[1,0]
	v_pk_mul_f32 v[54:55], v[54:55], v[68:69] op_sel_hi:[1,0]
	v_pk_mul_f32 v[52:53], v[52:53], v[68:69] op_sel_hi:[1,0]
	v_pk_mul_f32 v[50:51], v[50:51], v[68:69] op_sel_hi:[1,0]
	v_pk_mul_f32 v[48:49], v[48:49], v[68:69] op_sel_hi:[1,0]
	v_pk_mul_f32 v[46:47], v[46:47], v[68:69] op_sel_hi:[1,0]
	v_pk_mul_f32 v[44:45], v[44:45], v[68:69] op_sel_hi:[1,0]
	v_pk_mul_f32 v[42:43], v[42:43], v[68:69] op_sel_hi:[1,0]
	v_pk_mul_f32 v[40:41], v[40:41], v[68:69] op_sel_hi:[1,0]
	v_pk_mul_f32 v[38:39], v[38:39], v[68:69] op_sel_hi:[1,0]
	v_pk_mul_f32 v[36:37], v[36:37], v[68:69] op_sel_hi:[1,0]
	v_pk_mul_f32 v[34:35], v[34:35], v[68:69] op_sel_hi:[1,0]
	v_pk_mul_f32 v[32:33], v[32:33], v[68:69] op_sel_hi:[1,0]
	v_pk_mul_f32 v[30:31], v[30:31], v[68:69] op_sel_hi:[1,0]
	v_pk_mul_f32 v[28:29], v[28:29], v[68:69] op_sel_hi:[1,0]
	v_pk_mul_f32 v[26:27], v[26:27], v[68:69] op_sel_hi:[1,0]
	v_pk_mul_f32 v[24:25], v[24:25], v[68:69] op_sel_hi:[1,0]
	v_pk_mul_f32 v[22:23], v[22:23], v[68:69] op_sel_hi:[1,0]
	v_pk_mul_f32 v[20:21], v[20:21], v[68:69] op_sel_hi:[1,0]
	v_pk_mul_f32 v[18:19], v[18:19], v[68:69] op_sel_hi:[1,0]
	v_pk_mul_f32 v[16:17], v[16:17], v[68:69] op_sel_hi:[1,0]
	v_pk_mul_f32 v[14:15], v[14:15], v[68:69] op_sel_hi:[1,0]
	v_pk_mul_f32 v[12:13], v[12:13], v[68:69] op_sel_hi:[1,0]
	v_pk_mul_f32 v[10:11], v[10:11], v[68:69] op_sel_hi:[1,0]
	v_pk_mul_f32 v[8:9], v[8:9], v[68:69] op_sel_hi:[1,0]
	v_pk_mul_f32 v[6:7], v[6:7], v[68:69] op_sel_hi:[1,0]
	v_pk_mul_f32 v[4:5], v[4:5], v[68:69] op_sel_hi:[1,0]
	v_pk_mul_f32 v[2:3], v[2:3], v[68:69] op_sel_hi:[1,0]
	v_pk_mul_f32 v[0:1], v[0:1], v[68:69] op_sel_hi:[1,0]
	v_pk_add_f32 v[82:83], v[82:83], v[66:67] op_sel_hi:[1,0] neg_lo:[0,1] neg_hi:[0,1]
	v_pk_add_f32 v[84:85], v[84:85], v[66:67] op_sel_hi:[1,0] neg_lo:[0,1] neg_hi:[0,1]
	v_pk_add_f32 v[86:87], v[86:87], v[66:67] op_sel_hi:[1,0] neg_lo:[0,1] neg_hi:[0,1]
	v_pk_add_f32 v[88:89], v[88:89], v[66:67] op_sel_hi:[1,0] neg_lo:[0,1] neg_hi:[0,1]
	v_pk_add_f32 v[90:91], v[90:91], v[66:67] op_sel_hi:[1,0] neg_lo:[0,1] neg_hi:[0,1]
	v_pk_add_f32 v[92:93], v[92:93], v[66:67] op_sel_hi:[1,0] neg_lo:[0,1] neg_hi:[0,1]
	v_pk_add_f32 v[94:95], v[94:95], v[66:67] op_sel_hi:[1,0] neg_lo:[0,1] neg_hi:[0,1]
	v_mul_f32_e32 v96, v96, v68
	v_mov_b32_e32 v65, v64
	v_mov_b32_e32 v66, v64
	v_mov_b32_e32 v67, v64
	v_mov_b32_e32 v68, v64
	v_mov_b32_e32 v69, v64
	v_mov_b32_e32 v70, v64
	v_mov_b32_e32 v71, v64
	v_mov_b32_e32 v72, v64
	v_mov_b32_e32 v73, v64
	v_mov_b32_e32 v74, v64
	v_mov_b32_e32 v75, v64
	v_mov_b32_e32 v76, v64
	v_mov_b32_e32 v77, v64
	v_mov_b32_e32 v78, v64
	v_mov_b32_e32 v79, v64
.Lmla_b_norescale:
	v_exp_f32_e32 v80, v80
	v_exp_f32_e32 v81, v81
	v_exp_f32_e32 v82, v82
	v_exp_f32_e32 v83, v83
	v_add_f32_e32 v97, 0, v80
	v_exp_f32_e32 v98, v84
	v_add_f32_e32 v97, v81, v97
	v_add_f32_e32 v97, v82, v97
	v_add_f32_e32 v97, v83, v97
	v_add_f32_e32 v84, v98, v97
	v_exp_f32_e32 v97, v85
	v_exp_f32_e32 v99, v86
	v_exp_f32_e32 v87, v87
	v_exp_f32_e32 v88, v88
	v_add_f32_e32 v84, v97, v84
	v_exp_f32_e32 v89, v89
	v_add_f32_e32 v84, v99, v84
	v_exp_f32_e32 v90, v90
	v_add_f32_e32 v84, v87, v84
	v_exp_f32_e32 v91, v91
	v_add_f32_e32 v84, v88, v84
	v_exp_f32_e32 v92, v92
	v_add_f32_e32 v84, v89, v84
	v_exp_f32_e32 v93, v93
	v_add_f32_e32 v84, v90, v84
	v_exp_f32_e32 v94, v94
	v_add_f32_e32 v84, v91, v84
	v_exp_f32_e32 v95, v95
	v_add_f32_e32 v84, v92, v84
	v_add_f32_e32 v84, v93, v84
	v_add_f32_e32 v84, v94, v84
	v_cvt_pk_bf16_f32 v85, v82, v83
	v_cvt_pk_bf16_f32 v82, v92, v93
	v_add_f32_e32 v100, v95, v84
	v_cvt_pk_bf16_f32 v84, v80, v81
	v_cvt_pk_bf16_f32 v80, v88, v89
	v_cvt_pk_bf16_f32 v81, v90, v91
	v_cvt_pk_bf16_f32 v86, v98, v97
	v_cvt_pk_bf16_f32 v87, v99, v87
	v_cvt_pk_bf16_f32 v83, v94, v95
	v_add_f32_e32 v164, v96, v100
	s_waitcnt lgkmcnt(3)
	v_mfma_f32_32x32x16_bf16 v[48:63], v[216:219], v[84:87], v[48:63]
	ds_read_b128 v[232:235], v207 offset:24576
	s_waitcnt lgkmcnt(3)
	v_mfma_f32_32x32x16_bf16 v[32:47], v[220:223], v[84:87], v[32:47]
	ds_read_b128 v[236:239], v207 offset:28672
	s_waitcnt lgkmcnt(3)
	v_mfma_f32_32x32x16_bf16 v[16:31], v[224:227], v[84:87], v[16:31]
	ds_read_b128 v[240:243], v207 offset:32768
	s_waitcnt lgkmcnt(3)
	v_mfma_f32_32x32x16_bf16 v[0:15], v[228:231], v[84:87], v[0:15]
	ds_read_b128 v[248:251], v207 offset:36864
	s_waitcnt lgkmcnt(3)
	v_mfma_f32_32x32x16_bf16 v[48:63], v[232:235], v[80:83], v[48:63]
	s_waitcnt lgkmcnt(2)
	v_mfma_f32_32x32x16_bf16 v[32:47], v[236:239], v[80:83], v[32:47]
	s_waitcnt lgkmcnt(1)
	v_mfma_f32_32x32x16_bf16 v[16:31], v[240:243], v[80:83], v[16:31]
	s_waitcnt lgkmcnt(0)
	v_mfma_f32_32x32x16_bf16 v[0:15], v[248:251], v[80:83], v[0:15]
	s_cmp_lg_u32 s14, s23
	s_cbranch_scc1 .LBB0_556
	ds_bpermute_b32 v64, v183, v164
	s_lshl_b32 s54, s21, 1
	v_lshlrev_b32_e32 v176, 3, v174
	s_waitcnt vmcnt(0) lgkmcnt(0)
	s_barrier
	v_add_f32_e32 v64, v164, v64
	v_div_scale_f32 v65, s[0:1], v64, v64, 1.0
	v_rcp_f32_e32 v66, v65
	v_div_scale_f32 v67, vcc, 1.0, v64, 1.0
	v_fma_f32 v68, -v65, v66, 1.0
	v_fmac_f32_e32 v66, v68, v66
	v_mul_f32_e32 v68, v67, v66
	v_fma_f32 v69, -v65, v68, v67
	v_fmac_f32_e32 v68, v69, v66
	v_fma_f32 v65, -v65, v68, v67
	v_div_fmas_f32 v65, v65, v66, v68
	v_mov_b64_e32 v[66:67], s[12:13]
	v_div_fixup_f32 v64, v65, v64, 1.0
	v_mad_i64_i32 v[66:67], s[0:1], v175, s78, v[66:67]
	v_lshl_add_u64 v[66:67], v[66:67], 0, s[54:55]
	v_pk_mul_f32 v[48:49], v[48:49], v[64:65] op_sel_hi:[1,0]
	v_pk_mul_f32 v[50:51], v[50:51], v[64:65] op_sel_hi:[1,0]
	v_pk_mul_f32 v[32:33], v[32:33], v[64:65] op_sel_hi:[1,0]
	v_pk_mul_f32 v[34:35], v[34:35], v[64:65] op_sel_hi:[1,0]
	v_pk_mul_f32 v[16:17], v[16:17], v[64:65] op_sel_hi:[1,0]
	v_pk_mul_f32 v[18:19], v[18:19], v[64:65] op_sel_hi:[1,0]
	v_pk_mul_f32 v[0:1], v[0:1], v[64:65] op_sel_hi:[1,0]
	v_pk_mul_f32 v[2:3], v[2:3], v[64:65] op_sel_hi:[1,0]
	v_lshl_add_u64 v[66:67], v[66:67], 0, v[176:177]
	v_cvt_pk_bf16_f32 v48, v48, v49
	v_cvt_pk_bf16_f32 v49, v50, v51
	v_cvt_pk_bf16_f32 v32, v32, v33
	v_cvt_pk_bf16_f32 v33, v34, v35
	v_cvt_pk_bf16_f32 v16, v16, v17
	v_cvt_pk_bf16_f32 v17, v18, v19
	v_cvt_pk_bf16_f32 v0, v0, v1
	v_cvt_pk_bf16_f32 v1, v2, v3
	global_store_dwordx2 v[66:67], v[48:49], off
	v_pk_mul_f32 v[48:49], v[52:53], v[64:65] op_sel_hi:[1,0]
	v_pk_mul_f32 v[50:51], v[54:55], v[64:65] op_sel_hi:[1,0]
	global_store_dwordx2 v[66:67], v[32:33], off offset:64
	v_pk_mul_f32 v[32:33], v[36:37], v[64:65] op_sel_hi:[1,0]
	v_pk_mul_f32 v[34:35], v[38:39], v[64:65] op_sel_hi:[1,0]
	global_store_dwordx2 v[66:67], v[16:17], off offset:128
	v_pk_mul_f32 v[16:17], v[20:21], v[64:65] op_sel_hi:[1,0]
	v_pk_mul_f32 v[18:19], v[22:23], v[64:65] op_sel_hi:[1,0]
	global_store_dwordx2 v[66:67], v[0:1], off offset:192
	v_pk_mul_f32 v[0:1], v[4:5], v[64:65] op_sel_hi:[1,0]
	v_pk_mul_f32 v[2:3], v[6:7], v[64:65] op_sel_hi:[1,0]
	v_cvt_pk_bf16_f32 v48, v48, v49
	v_cvt_pk_bf16_f32 v49, v50, v51
	v_cvt_pk_bf16_f32 v32, v32, v33
	v_cvt_pk_bf16_f32 v33, v34, v35
	v_cvt_pk_bf16_f32 v16, v16, v17
	v_cvt_pk_bf16_f32 v17, v18, v19
	v_cvt_pk_bf16_f32 v0, v0, v1
	v_cvt_pk_bf16_f32 v1, v2, v3
	global_store_dwordx2 v[66:67], v[48:49], off offset:16
	v_pk_mul_f32 v[48:49], v[56:57], v[64:65] op_sel_hi:[1,0]
	v_pk_mul_f32 v[50:51], v[58:59], v[64:65] op_sel_hi:[1,0]
	global_store_dwordx2 v[66:67], v[32:33], off offset:80
	v_pk_mul_f32 v[32:33], v[40:41], v[64:65] op_sel_hi:[1,0]
	v_pk_mul_f32 v[34:35], v[42:43], v[64:65] op_sel_hi:[1,0]
	global_store_dwordx2 v[66:67], v[16:17], off offset:144
	v_pk_mul_f32 v[16:17], v[24:25], v[64:65] op_sel_hi:[1,0]
	v_pk_mul_f32 v[18:19], v[26:27], v[64:65] op_sel_hi:[1,0]
	global_store_dwordx2 v[66:67], v[0:1], off offset:208
	v_pk_mul_f32 v[0:1], v[8:9], v[64:65] op_sel_hi:[1,0]
	v_pk_mul_f32 v[2:3], v[10:11], v[64:65] op_sel_hi:[1,0]
	v_cvt_pk_bf16_f32 v48, v48, v49
	v_cvt_pk_bf16_f32 v49, v50, v51
	v_cvt_pk_bf16_f32 v32, v32, v33
	v_cvt_pk_bf16_f32 v33, v34, v35
	v_cvt_pk_bf16_f32 v16, v16, v17
	v_cvt_pk_bf16_f32 v17, v18, v19
	v_cvt_pk_bf16_f32 v0, v0, v1
	v_cvt_pk_bf16_f32 v1, v2, v3
	global_store_dwordx2 v[66:67], v[48:49], off offset:32
	v_pk_mul_f32 v[48:49], v[60:61], v[64:65] op_sel_hi:[1,0]
	v_pk_mul_f32 v[50:51], v[62:63], v[64:65] op_sel_hi:[1,0]
	global_store_dwordx2 v[66:67], v[32:33], off offset:96
	v_pk_mul_f32 v[32:33], v[44:45], v[64:65] op_sel_hi:[1,0]
	v_pk_mul_f32 v[34:35], v[46:47], v[64:65] op_sel_hi:[1,0]
	global_store_dwordx2 v[66:67], v[16:17], off offset:160
	v_pk_mul_f32 v[16:17], v[28:29], v[64:65] op_sel_hi:[1,0]
	v_pk_mul_f32 v[18:19], v[30:31], v[64:65] op_sel_hi:[1,0]
	global_store_dwordx2 v[66:67], v[0:1], off offset:224
	v_pk_mul_f32 v[0:1], v[12:13], v[64:65] op_sel_hi:[1,0]
	v_pk_mul_f32 v[2:3], v[14:15], v[64:65] op_sel_hi:[1,0]
	s_add_i32 s20, s20, s36
	s_add_i32 s11, s11, s36
	v_cvt_pk_bf16_f32 v48, v48, v49
	v_cvt_pk_bf16_f32 v49, v50, v51
	v_cvt_pk_bf16_f32 v32, v32, v33
	v_cvt_pk_bf16_f32 v33, v34, v35
	v_cvt_pk_bf16_f32 v16, v16, v17
	v_cvt_pk_bf16_f32 v17, v18, v19
	v_cvt_pk_bf16_f32 v0, v0, v1
	v_cvt_pk_bf16_f32 v1, v2, v3
	s_cmp_ge_i32 s20, s10
	global_store_dwordx2 v[66:67], v[48:49], off offset:48
	global_store_dwordx2 v[66:67], v[32:33], off offset:112
	global_store_dwordx2 v[66:67], v[16:17], off offset:176
	global_store_dwordx2 v[66:67], v[0:1], off offset:240
	s_cbranch_scc0 .LBB0_541
